# peel5 + hand-written QKV head-norm statistics path (packed squares, permlane-swap batched row reduction, pipelined LDS reads, bare v_rsq)
# speedup vs baseline: 1.0330x; 1.0140x over previous
; __device__ __forceinline__ float shx(float v, int lane, int mask) { return __builtin_bit_cast(float, __builtin_amdgcn_ds_bpermute((lane ^ mask) << 2, __builtin_bit_cast(int, v))); }
; #define PG8_XBAR() do { asm volatile("s_waitcnt lgkmcnt(0)" ::: "memory"); __builtin_amdgcn_s_barrier(); asm volatile("" ::: "memory"); } while (0)
;     __device__ __forceinline__ void operator()(AccT& acc, const Unit& u, int wr, int wc, int fr, int fq, PG8_LAS unsigned char* lds) const {
;     ...
;                 for (int m = 0; m < 4; ++m) { float s[2];
; #pragma unroll
;                     for (int bj = 0; bj < 2; ++bj) { const f32x4 a = acc[ai][bj][m][0], b = acc[ai][bj][m][1];
;                         s[bj] = ((a.x * a.x + a.y * a.y) + (a.z * a.z + a.w * a.w)) + ((b.x * b.x + b.y * b.y) + (b.z * b.z + b.w * b.w)); }
;                     if (NSEG == 1) { s[0] += s[1]; s[1] = 0.f; }
; #pragma unroll
;                     for (int sg = 0; sg < NSEG; ++sg) { float t = s[sg]; t += shx(t, fr + 16 * fq, 16); t += shx(t, fr + 16 * fq, 32);
;                         if (fq == 0) P[((ai * HALF + wr * 64 + m * 16 + fr) * 2 + sg) * 4 + wc] = t; } }
;             PG8_XBAR();
.LBB0_732:
	ds_read2_b32 v[162:163], v191 offset1:16
	ds_read2_b32 v[160:161], v191 offset0:32 offset1:48
	ds_read2_b32 v[158:159], v191 offset0:128 offset1:144
	ds_read2_b32 v[156:157], v191 offset0:160 offset1:176
	s_and_b64 vcc, exec, s[42:43]
	s_cbranch_vccnz .LBB0_766
	v_pk_mul_f32 v[180:181], v[124:125], v[124:125]
	v_pk_fma_f32 v[180:181], v[126:127], v[126:127], v[180:181]
	v_pk_fma_f32 v[180:181], v[120:121], v[120:121], v[180:181]
	v_pk_fma_f32 v[180:181], v[122:123], v[122:123], v[180:181]
	v_add_f32_e32 v164, v180, v181
	v_pk_mul_f32 v[182:183], v[116:117], v[116:117]
	v_pk_fma_f32 v[182:183], v[118:119], v[118:119], v[182:183]
	v_pk_fma_f32 v[182:183], v[108:109], v[108:109], v[182:183]
	v_pk_fma_f32 v[182:183], v[110:111], v[110:111], v[182:183]
	v_add_f32_e32 v165, v182, v183
	v_pk_mul_f32 v[192:193], v[112:113], v[112:113]
	v_pk_fma_f32 v[192:193], v[114:115], v[114:115], v[192:193]
	v_pk_fma_f32 v[192:193], v[104:105], v[104:105], v[192:193]
	v_pk_fma_f32 v[192:193], v[106:107], v[106:107], v[192:193]
	v_add_f32_e32 v166, v192, v193
	v_pk_mul_f32 v[194:195], v[100:101], v[100:101]
	v_pk_fma_f32 v[194:195], v[102:103], v[102:103], v[194:195]
	v_pk_fma_f32 v[194:195], v[92:93], v[92:93], v[194:195]
	v_pk_fma_f32 v[194:195], v[94:95], v[94:95], v[194:195]
	v_add_f32_e32 v167, v194, v195
	v_pk_mul_f32 v[180:181], v[96:97], v[96:97]
	v_pk_fma_f32 v[180:181], v[98:99], v[98:99], v[180:181]
	v_pk_fma_f32 v[180:181], v[88:89], v[88:89], v[180:181]
	v_pk_fma_f32 v[180:181], v[90:91], v[90:91], v[180:181]
	v_add_f32_e32 v168, v180, v181
	v_pk_mul_f32 v[182:183], v[84:85], v[84:85]
	v_pk_fma_f32 v[182:183], v[86:87], v[86:87], v[182:183]
	v_pk_fma_f32 v[182:183], v[76:77], v[76:77], v[182:183]
	v_pk_fma_f32 v[182:183], v[78:79], v[78:79], v[182:183]
	v_add_f32_e32 v169, v182, v183
	v_pk_mul_f32 v[192:193], v[80:81], v[80:81]
	v_pk_fma_f32 v[192:193], v[82:83], v[82:83], v[192:193]
	v_pk_fma_f32 v[192:193], v[72:73], v[72:73], v[192:193]
	v_pk_fma_f32 v[192:193], v[74:75], v[74:75], v[192:193]
	v_add_f32_e32 v170, v192, v193
	v_pk_mul_f32 v[194:195], v[68:69], v[68:69]
	v_pk_fma_f32 v[194:195], v[70:71], v[70:71], v[194:195]
	v_pk_fma_f32 v[194:195], v[64:65], v[64:65], v[194:195]
	v_pk_fma_f32 v[194:195], v[66:67], v[66:67], v[194:195]
	v_add_f32_e32 v171, v194, v195
	v_pk_mul_f32 v[180:181], v[60:61], v[60:61]
	v_pk_fma_f32 v[180:181], v[62:63], v[62:63], v[180:181]
	v_pk_fma_f32 v[180:181], v[56:57], v[56:57], v[180:181]
	v_pk_fma_f32 v[180:181], v[58:59], v[58:59], v[180:181]
	v_add_f32_e32 v172, v180, v181
	v_pk_mul_f32 v[182:183], v[52:53], v[52:53]
	v_pk_fma_f32 v[182:183], v[54:55], v[54:55], v[182:183]
	v_pk_fma_f32 v[182:183], v[44:45], v[44:45], v[182:183]
	v_pk_fma_f32 v[182:183], v[46:47], v[46:47], v[182:183]
	v_add_f32_e32 v173, v182, v183
	v_pk_mul_f32 v[192:193], v[48:49], v[48:49]
	v_pk_fma_f32 v[192:193], v[50:51], v[50:51], v[192:193]
	v_pk_fma_f32 v[192:193], v[40:41], v[40:41], v[192:193]
	v_pk_fma_f32 v[192:193], v[42:43], v[42:43], v[192:193]
	v_add_f32_e32 v174, v192, v193
	v_pk_mul_f32 v[194:195], v[36:37], v[36:37]
	v_pk_fma_f32 v[194:195], v[38:39], v[38:39], v[194:195]
	v_pk_fma_f32 v[194:195], v[28:29], v[28:29], v[194:195]
	v_pk_fma_f32 v[194:195], v[30:31], v[30:31], v[194:195]
	v_add_f32_e32 v175, v194, v195
	v_pk_mul_f32 v[180:181], v[32:33], v[32:33]
	v_pk_fma_f32 v[180:181], v[34:35], v[34:35], v[180:181]
	v_pk_fma_f32 v[180:181], v[24:25], v[24:25], v[180:181]
	v_pk_fma_f32 v[180:181], v[26:27], v[26:27], v[180:181]
	v_add_f32_e32 v176, v180, v181
	v_pk_mul_f32 v[182:183], v[20:21], v[20:21]
	v_pk_fma_f32 v[182:183], v[22:23], v[22:23], v[182:183]
	v_pk_fma_f32 v[182:183], v[12:13], v[12:13], v[182:183]
	v_pk_fma_f32 v[182:183], v[14:15], v[14:15], v[182:183]
	v_add_f32_e32 v177, v182, v183
	v_pk_mul_f32 v[192:193], v[16:17], v[16:17]
	v_pk_fma_f32 v[192:193], v[18:19], v[18:19], v[192:193]
	v_pk_fma_f32 v[192:193], v[8:9], v[8:9], v[192:193]
	v_pk_fma_f32 v[192:193], v[10:11], v[10:11], v[192:193]
	v_add_f32_e32 v178, v192, v193
	v_pk_mul_f32 v[194:195], v[4:5], v[4:5]
	v_pk_fma_f32 v[194:195], v[6:7], v[6:7], v[194:195]
	v_pk_fma_f32 v[194:195], v[0:1], v[0:1], v[194:195]
	v_pk_fma_f32 v[194:195], v[2:3], v[2:3], v[194:195]
	v_add_f32_e32 v179, v194, v195
	v_mbcnt_lo_u32_b32 v197, -1, 0
	v_mbcnt_hi_u32_b32 v197, -1, v197
	v_and_b32_e32 v198, 32, v197
	v_and_b32_e32 v199, 16, v197
	v_lshl_or_b32 v198, v198, 4, v199
	v_add3_u32 v198, v188, v198, s55
	v_permlane16_swap_b32_e32 v164, v165
	v_permlane16_swap_b32_e32 v166, v167
	v_permlane16_swap_b32_e32 v168, v169
	v_permlane16_swap_b32_e32 v170, v171
	v_permlane16_swap_b32_e32 v172, v173
	v_permlane16_swap_b32_e32 v174, v175
	v_permlane16_swap_b32_e32 v176, v177
	v_permlane16_swap_b32_e32 v178, v179
	v_add_f32_e32 v164, v164, v165
	v_add_f32_e32 v166, v166, v167
	v_add_f32_e32 v168, v168, v169
	v_add_f32_e32 v170, v170, v171
	v_add_f32_e32 v172, v172, v173
	v_add_f32_e32 v174, v174, v175
	v_add_f32_e32 v176, v176, v177
	v_add_f32_e32 v178, v178, v179
	v_permlane32_swap_b32_e32 v164, v166
	v_permlane32_swap_b32_e32 v168, v170
	v_permlane32_swap_b32_e32 v172, v174
	v_permlane32_swap_b32_e32 v176, v178
	v_add_f32_e32 v164, v164, v166
	v_add_f32_e32 v168, v168, v170
	v_add_f32_e32 v172, v172, v174
	v_add_f32_e32 v176, v176, v178
	ds_write_b32 v198, v164
	ds_write_b32 v198, v168 offset:1024
	ds_write_b32 v198, v172 offset:4096
	ds_write_b32 v198, v176 offset:5120
	s_waitcnt lgkmcnt(0)
	s_barrier
; #define PG8_LAS __attribute__((address_space(3)))
;     __device__ __forceinline__ void operator()(AccT& acc, const Unit& u, int wr, int wc, int fr, int fq, PG8_LAS unsigned char* lds) const {
;     ...
; #pragma unroll
;             for (int ai = 0; ai < 2; ++ai)
; #pragma unroll
;                 for (int m = 0; m < 4; ++m)
; #pragma unroll
;                     for (int sg = 0; sg < NSEG; ++sg) { const f32x4 t = *(const PG8_LAS f32x4*)(P + ((ai * HALF + wr * 64 + m * 16 + fr) * 2 + sg) * 4);
;                         const float r0 = rs[ai][m]; rn[ai][m][sg] = rsqrtf(((t.x + t.y) + (t.z + t.w)) * (r0 * r0) * (NSEG == 1 ? 1.0f / 256.f : 1.0f / 128.f) + 1e-6f) * (psc * r0); }
	v_add_u32_e32 v199, 0x20000, v188
	v_mov_b32_e32 v197, 0x3e0293ee
	v_cndmask_b32_e64 v197, 1.0, v197, s[40:41]
	ds_read_b128 v[180:183], v199
	ds_read_b128 v[192:195], v199 offset:16
	ds_read_b128 v[200:203], v199 offset:512
	ds_read_b128 v[204:207], v199 offset:528
	ds_read_b128 v[218:221], v199 offset:1024
	ds_read_b128 v[222:225], v199 offset:1040
	s_waitcnt lgkmcnt(4)
	v_mul_f32_e32 v196, v162, v162
	v_mul_f32_e32 v198, v197, v162
	v_mul_f32_e32 v196, 0x3c000000, v196
	v_pk_add_f32 v[180:181], v[180:181], v[182:183]
	v_pk_add_f32 v[192:193], v[192:193], v[194:195]
	v_add_f32_e32 v180, v180, v181
	v_add_f32_e32 v192, v192, v193
	v_fmaak_f32 v180, v180, v196, 0x358637bd
	v_fmaak_f32 v192, v192, v196, 0x358637bd
	v_rsq_f32_e32 v180, v180
	v_rsq_f32_e32 v192, v192
	v_mul_f32_e32 v164, v180, v198
	v_mul_f32_e32 v162, v192, v198
	ds_read_b128 v[180:183], v199 offset:1536
	ds_read_b128 v[192:195], v199 offset:1552
	s_waitcnt lgkmcnt(4)
	v_mul_f32_e32 v196, v163, v163
	v_mul_f32_e32 v198, v197, v163
	v_mul_f32_e32 v196, 0x3c000000, v196
	v_pk_add_f32 v[200:201], v[200:201], v[202:203]
	v_pk_add_f32 v[204:205], v[204:205], v[206:207]
	v_add_f32_e32 v200, v200, v201
	v_add_f32_e32 v204, v204, v205
	v_fmaak_f32 v200, v200, v196, 0x358637bd
	v_fmaak_f32 v204, v204, v196, 0x358637bd
	v_rsq_f32_e32 v200, v200
	v_rsq_f32_e32 v204, v204
	v_mul_f32_e32 v166, v200, v198
	v_mul_f32_e32 v163, v204, v198
	ds_read_b128 v[200:203], v199 offset:4096
	ds_read_b128 v[204:207], v199 offset:4112
	s_waitcnt lgkmcnt(4)
	v_mul_f32_e32 v196, v160, v160
	v_mul_f32_e32 v198, v197, v160
	v_mul_f32_e32 v196, 0x3c000000, v196
	v_pk_add_f32 v[218:219], v[218:219], v[220:221]
	v_pk_add_f32 v[222:223], v[222:223], v[224:225]
	v_add_f32_e32 v218, v218, v219
	v_add_f32_e32 v222, v222, v223
	v_fmaak_f32 v218, v218, v196, 0x358637bd
	v_fmaak_f32 v222, v222, v196, 0x358637bd
	v_rsq_f32_e32 v218, v218
	v_rsq_f32_e32 v222, v222
	v_mul_f32_e32 v168, v218, v198
	v_mul_f32_e32 v160, v222, v198
	ds_read_b128 v[218:221], v199 offset:4608
	ds_read_b128 v[222:225], v199 offset:4624
	s_waitcnt lgkmcnt(4)
	v_mul_f32_e32 v196, v161, v161
	v_mul_f32_e32 v198, v197, v161
	v_mul_f32_e32 v196, 0x3c000000, v196
	v_pk_add_f32 v[180:181], v[180:181], v[182:183]
	v_pk_add_f32 v[192:193], v[192:193], v[194:195]
	v_add_f32_e32 v180, v180, v181
	v_add_f32_e32 v192, v192, v193
	v_fmaak_f32 v180, v180, v196, 0x358637bd
	v_fmaak_f32 v192, v192, v196, 0x358637bd
	v_rsq_f32_e32 v180, v180
	v_rsq_f32_e32 v192, v192
	v_mul_f32_e32 v170, v180, v198
	v_mul_f32_e32 v161, v192, v198
	ds_read_b128 v[180:183], v199 offset:5120
	ds_read_b128 v[192:195], v199 offset:5136
	s_waitcnt lgkmcnt(4)
	v_mul_f32_e32 v196, v158, v158
	v_mul_f32_e32 v198, v197, v158
	v_mul_f32_e32 v196, 0x3c000000, v196
	v_pk_add_f32 v[200:201], v[200:201], v[202:203]
	v_pk_add_f32 v[204:205], v[204:205], v[206:207]
	v_add_f32_e32 v200, v200, v201
	v_add_f32_e32 v204, v204, v205
	v_fmaak_f32 v200, v200, v196, 0x358637bd
	v_fmaak_f32 v204, v204, v196, 0x358637bd
	v_rsq_f32_e32 v200, v200
	v_rsq_f32_e32 v204, v204
	v_mul_f32_e32 v172, v200, v198
	v_mul_f32_e32 v158, v204, v198
	ds_read_b128 v[200:203], v199 offset:5632
	ds_read_b128 v[204:207], v199 offset:5648
	s_waitcnt lgkmcnt(4)
	v_mul_f32_e32 v196, v159, v159
	v_mul_f32_e32 v198, v197, v159
	v_mul_f32_e32 v196, 0x3c000000, v196
	v_pk_add_f32 v[218:219], v[218:219], v[220:221]
	v_pk_add_f32 v[222:223], v[222:223], v[224:225]
	v_add_f32_e32 v218, v218, v219
	v_add_f32_e32 v222, v222, v223
	v_fmaak_f32 v218, v218, v196, 0x358637bd
	v_fmaak_f32 v222, v222, v196, 0x358637bd
	v_rsq_f32_e32 v218, v218
	v_rsq_f32_e32 v222, v222
	v_mul_f32_e32 v174, v218, v198
	v_mul_f32_e32 v159, v222, v198
	s_waitcnt lgkmcnt(2)
	v_mul_f32_e32 v196, v156, v156
	v_mul_f32_e32 v198, v197, v156
	v_mul_f32_e32 v196, 0x3c000000, v196
	v_pk_add_f32 v[180:181], v[180:181], v[182:183]
	v_pk_add_f32 v[192:193], v[192:193], v[194:195]
	v_add_f32_e32 v180, v180, v181
	v_add_f32_e32 v192, v192, v193
	v_fmaak_f32 v180, v180, v196, 0x358637bd
	v_fmaak_f32 v192, v192, v196, 0x358637bd
	v_rsq_f32_e32 v180, v180
	v_rsq_f32_e32 v192, v192
	v_mul_f32_e32 v178, v180, v198
	v_mul_f32_e32 v156, v192, v198
	s_waitcnt lgkmcnt(0)
	v_mul_f32_e32 v196, v157, v157
	v_mul_f32_e32 v198, v197, v157
	v_mul_f32_e32 v196, 0x3c000000, v196
	v_pk_add_f32 v[200:201], v[200:201], v[202:203]
	v_pk_add_f32 v[204:205], v[204:205], v[206:207]
	v_add_f32_e32 v200, v200, v201
	v_add_f32_e32 v204, v204, v205
	v_fmaak_f32 v200, v200, v196, 0x358637bd
	v_fmaak_f32 v204, v204, v196, 0x358637bd
	v_rsq_f32_e32 v200, v200
	v_rsq_f32_e32 v204, v204
	v_mul_f32_e32 v176, v200, v198
	v_mul_f32_e32 v157, v204, v198
	s_branch .LBB0_767
